# grid barrier: XCD leader releases the local generation before its own acquire invalidate
# speedup vs baseline: 1.0277x; 1.0076x over previous
.LBB0_156:
	s_or_b64 exec, exec, s[36:37]
	s_waitcnt vmcnt(0)
	global_atomic_add v[174:175], v190, off
	buffer_inv sc1
	s_waitcnt vmcnt(0)

.LBB0_431:
	s_or_b64 exec, exec, s[38:39]
	s_waitcnt vmcnt(0)
	global_atomic_add v[174:175], v190, off
	buffer_inv sc1
	s_waitcnt vmcnt(0)

.LBB0_942:
	s_or_b64 exec, exec, s[40:41]
	s_waitcnt vmcnt(0)
	global_atomic_add v[174:175], v190, off
	buffer_inv sc1
	s_waitcnt vmcnt(0)
